# zero-init of the 128 accumulators with 64 v_mov_b64 instead of 128 v_mov_b32 (in-proj, up-proj), on top of the previous best
# speedup vs baseline: 1.0042x; 1.0042x over previous
;     __device__ __forceinline__ void init(f32x4 (&acc)[2][2][4][2], const Unit&, int, int, int, int) const {
; #pragma unroll
;         for (int a = 0; a < 2; ++a)
; #pragma unroll
;             for (int b = 0; b < 2; ++b)
; #pragma unroll
;                 for (int m = 0; m < 4; ++m)
; #pragma unroll
;                     for (int n = 0; n < 2; ++n) acc[a][b][m][n] = (f32x4){0.f, 0.f, 0.f, 0.f};
;     }
; template <class Epi, class Sched, bool ALIGN_EPI = false, bool SP2 = false>
; __device__ __forceinline__ void gemm_phase(PG8_LAS unsigned char* lds, const Gemm g, const Sched& S, const Epi& E, const int wid_in) {
;     ...
;         const bool has_next = S.next(ui + 1, nxt);
;         const char* nA = has_next ? (const char*)g.A + (size_t)nxt.pm * tstepA : cA; const char* nB = has_next ? (const char*)g.Bt + (size_t)nxt.pn * tstep : cB;
.LBB0_118:
	s_ashr_i32 s17, s16, 31
	s_lshl_b64 s[18:19], s[16:17], 20
	s_add_u32 s18, s28, s18
	s_addc_u32 s19, s29, s19
	s_and_b64 s[20:21], s[0:1], exec
	s_cselect_b32 s17, s19, s5
	s_cselect_b32 s42, s18, s4
	s_ashr_i32 s15, s14, 31
	s_lshl_b64 s[20:21], s[14:15], 20
	s_add_u32 s20, s30, s20
	s_addc_u32 s21, s31, s21
	s_and_b64 s[22:23], s[0:1], exec
	s_cselect_b32 s15, s21, s3
	s_cselect_b32 s43, s20, s2
	s_add_u32 s4, s4, 0x80080
	s_addc_u32 s5, s5, 0
	s_add_u32 s44, s2, 0x100
	s_addc_u32 s45, s3, 0
	s_mov_b32 s46, -2
	v_mov_b64_e32 v[2:3], 0
	v_mov_b64_e32 v[4:5], 0
	v_mov_b64_e32 v[6:7], 0
	v_mov_b64_e32 v[8:9], 0
	v_mov_b64_e32 v[10:11], 0
	v_mov_b64_e32 v[12:13], 0
	v_mov_b64_e32 v[14:15], 0
	v_mov_b64_e32 v[16:17], 0
	v_mov_b64_e32 v[18:19], 0
	v_mov_b64_e32 v[20:21], 0
	v_mov_b64_e32 v[22:23], 0
	v_mov_b64_e32 v[24:25], 0
	v_mov_b64_e32 v[26:27], 0
	v_mov_b64_e32 v[28:29], 0
	v_mov_b64_e32 v[30:31], 0
	v_mov_b64_e32 v[32:33], 0
	v_mov_b64_e32 v[34:35], 0
	v_mov_b64_e32 v[36:37], 0
	v_mov_b64_e32 v[38:39], 0
	v_mov_b64_e32 v[40:41], 0
	v_mov_b64_e32 v[42:43], 0
	v_mov_b64_e32 v[44:45], 0
	v_mov_b64_e32 v[46:47], 0
	v_mov_b64_e32 v[48:49], 0
	v_mov_b64_e32 v[50:51], 0
	v_mov_b64_e32 v[52:53], 0
	v_mov_b64_e32 v[54:55], 0
	v_mov_b64_e32 v[56:57], 0
	v_mov_b64_e32 v[58:59], 0
	v_mov_b64_e32 v[60:61], 0
	v_mov_b64_e32 v[62:63], 0
	v_mov_b64_e32 v[64:65], 0
	v_mov_b64_e32 v[66:67], 0
	v_mov_b64_e32 v[68:69], 0
	v_mov_b64_e32 v[70:71], 0
	v_mov_b64_e32 v[72:73], 0
	v_mov_b64_e32 v[74:75], 0
	v_mov_b64_e32 v[76:77], 0
	v_mov_b64_e32 v[78:79], 0
	v_mov_b64_e32 v[80:81], 0
	v_mov_b64_e32 v[82:83], 0
	v_mov_b64_e32 v[84:85], 0
	v_mov_b64_e32 v[86:87], 0
	v_mov_b64_e32 v[88:89], 0
	v_mov_b64_e32 v[90:91], 0
	v_mov_b64_e32 v[92:93], 0
	v_mov_b64_e32 v[94:95], 0
	v_mov_b64_e32 v[96:97], 0
	v_mov_b64_e32 v[98:99], 0
	v_mov_b64_e32 v[100:101], 0
	v_mov_b64_e32 v[102:103], 0
	v_mov_b64_e32 v[104:105], 0
	v_mov_b64_e32 v[106:107], 0
	v_mov_b64_e32 v[108:109], 0
	v_mov_b64_e32 v[110:111], 0
	v_mov_b64_e32 v[112:113], 0
	v_mov_b64_e32 v[114:115], 0
	v_mov_b64_e32 v[116:117], 0
	v_mov_b64_e32 v[118:119], 0
	v_mov_b64_e32 v[120:121], 0
	v_mov_b64_e32 v[122:123], 0
	v_mov_b64_e32 v[124:125], 0
	v_mov_b64_e32 v[126:127], 0
	v_mov_b64_e32 v[128:129], 0

;     __device__ __forceinline__ void init(f32x4 (&acc)[2][2][4][2], const Unit&, int, int, int, int) const {
; #pragma unroll
;         for (int a = 0; a < 2; ++a)
; #pragma unroll
;             for (int b = 0; b < 2; ++b)
; #pragma unroll
;                 for (int m = 0; m < 4; ++m)
; #pragma unroll
;                     for (int n = 0; n < 2; ++n) acc[a][b][m][n] = (f32x4){0.f, 0.f, 0.f, 0.f};
;     }
; template <class Epi, class Sched, bool ALIGN_EPI = false, bool SP2 = false>
; __device__ __forceinline__ void gemm_phase(PG8_LAS unsigned char* lds, const Gemm g, const Sched& S, const Epi& E, const int wid_in) {
;     ...
;         const bool has_next = S.next(ui + 1, nxt);
;         const char* nA = has_next ? (const char*)g.A + (size_t)nxt.pm * tstepA : cA; const char* nB = has_next ? (const char*)g.Bt + (size_t)nxt.pn * tstep : cB;
.LBB0_483:
	s_ashr_i32 s19, s18, 31
	s_lshl_b64 s[20:21], s[18:19], 20
	s_add_u32 s20, s30, s20
	s_addc_u32 s21, s31, s21
	s_and_b64 s[22:23], s[6:7], exec
	s_cselect_b32 s19, s21, s3
	s_cselect_b32 s44, s20, s2
	s_ashr_i32 s17, s16, 31
	s_lshl_b64 s[22:23], s[16:17], 20
	s_add_u32 s22, s33, s22
	s_addc_u32 s23, s34, s23
	s_and_b64 s[24:25], s[6:7], exec
	s_cselect_b32 s17, s23, s1
	s_cselect_b32 s45, s22, s0
	s_add_u32 s24, s2, 0x80080
	s_addc_u32 s25, s3, 0
	s_add_u32 s46, s0, 0x100
	s_addc_u32 s47, s1, 0
	s_mov_b32 s48, -2
	v_mov_b64_e32 v[2:3], 0
	v_mov_b64_e32 v[4:5], 0
	v_mov_b64_e32 v[6:7], 0
	v_mov_b64_e32 v[8:9], 0
	v_mov_b64_e32 v[10:11], 0
	v_mov_b64_e32 v[12:13], 0
	v_mov_b64_e32 v[14:15], 0
	v_mov_b64_e32 v[16:17], 0
	v_mov_b64_e32 v[18:19], 0
	v_mov_b64_e32 v[20:21], 0
	v_mov_b64_e32 v[22:23], 0
	v_mov_b64_e32 v[24:25], 0
	v_mov_b64_e32 v[26:27], 0
	v_mov_b64_e32 v[28:29], 0
	v_mov_b64_e32 v[30:31], 0
	v_mov_b64_e32 v[32:33], 0
	v_mov_b64_e32 v[34:35], 0
	v_mov_b64_e32 v[36:37], 0
	v_mov_b64_e32 v[38:39], 0
	v_mov_b64_e32 v[40:41], 0
	v_mov_b64_e32 v[42:43], 0
	v_mov_b64_e32 v[44:45], 0
	v_mov_b64_e32 v[46:47], 0
	v_mov_b64_e32 v[48:49], 0
	v_mov_b64_e32 v[50:51], 0
	v_mov_b64_e32 v[52:53], 0
	v_mov_b64_e32 v[54:55], 0
	v_mov_b64_e32 v[56:57], 0
	v_mov_b64_e32 v[58:59], 0
	v_mov_b64_e32 v[60:61], 0
	v_mov_b64_e32 v[62:63], 0
	v_mov_b64_e32 v[64:65], 0
	v_mov_b64_e32 v[66:67], 0
	v_mov_b64_e32 v[68:69], 0
	v_mov_b64_e32 v[70:71], 0
	v_mov_b64_e32 v[72:73], 0
	v_mov_b64_e32 v[74:75], 0
	v_mov_b64_e32 v[76:77], 0
	v_mov_b64_e32 v[78:79], 0
	v_mov_b64_e32 v[80:81], 0
	v_mov_b64_e32 v[82:83], 0
	v_mov_b64_e32 v[84:85], 0
	v_mov_b64_e32 v[86:87], 0
	v_mov_b64_e32 v[88:89], 0
	v_mov_b64_e32 v[90:91], 0
	v_mov_b64_e32 v[92:93], 0
	v_mov_b64_e32 v[94:95], 0
	v_mov_b64_e32 v[96:97], 0
	v_mov_b64_e32 v[98:99], 0
	v_mov_b64_e32 v[100:101], 0
	v_mov_b64_e32 v[102:103], 0
	v_mov_b64_e32 v[104:105], 0
	v_mov_b64_e32 v[106:107], 0
	v_mov_b64_e32 v[108:109], 0
	v_mov_b64_e32 v[110:111], 0
	v_mov_b64_e32 v[112:113], 0
	v_mov_b64_e32 v[114:115], 0
	v_mov_b64_e32 v[116:117], 0
	v_mov_b64_e32 v[118:119], 0
	v_mov_b64_e32 v[120:121], 0
	v_mov_b64_e32 v[122:123], 0
	v_mov_b64_e32 v[124:125], 0
	v_mov_b64_e32 v[126:127], 0
	v_mov_b64_e32 v[128:129], 0
